# v55 + tile raster WGM 8->2 in P2 and P7 (round = 2 token tiles x 16 column tiles)
# baseline (speedup 1.0000x reference)
;     __host__ __device__ bool next(int i, Unit& u) const {
;         const long L = (long)i * G + c; if (L >= nwg) return false;
;         int wgid = (int)L; { const int q = nwg / NXCD, r = nwg % NXCD, xcd = wgid % NXCD, off = wgid / NXCD; wgid = (xcd < r ? xcd * (q + 1) : r * (q + 1) + (xcd - r) * q) + off; }
;         const int nig = WGM * nN, gid = wgid / nig, fm = gid * WGM, gsz = (nM - fm) < WGM ? (nM - fm) : WGM;
;         u.pm = fm + ((wgid % nig) % gsz); u.pn = (wgid % nig) / gsz; return true;
; template <class Epi, class Sched, bool ALIGN_EPI = false, bool SP2 = false>
; __device__ __forceinline__ void gemm_phase(PG8_LAS unsigned char* lds, const Gemm g, const Sched& S, const Epi& E) {
;     ...
;     for (int i = 0; i < 2; ++i) { int R, C; stage_rc(tid * 16 + i * 8192, R, C); const int Rb = Epi::PERM ? ((R & ~31) + perm32(R & 31)) : R;
;         voffA[i] = (unsigned)(R * g.lda + C) * 2u; voffB[i] = (unsigned)(Rb * g.ldb + C) * 2u; }
;     const size_t kstep = (size_t)(BK * 2);
;     const size_t hstepA = (size_t)HALF * g.lda * 2, hstepB = (size_t)HALF * g.ldb * 2;
;     const size_t tstepA = 2 * hstepA, tstepB = 2 * hstepB, apn = (size_t)g.apn;
;     const unsigned ldsw = (unsigned)wid * 1024u;
;     const int aoff = lds_byte(wr * 64 + fr, fq * 8), boff = lds_byte(wc * 32 + fr, fq * 8);
;     ...
;     Unit cur, nxt; int ui = 0;
;     if (!S.next(0, cur)) return;
;     f32x4 acc[2][2][4][2];
; #pragma unroll
;     for (int a = 0; a < 2; ++a)
; #pragma unroll
;         for (int b = 0; b < 2; ++b)
; #pragma unroll
;             for (int m = 0; m < 4; ++m)
; #pragma unroll
;                 for (int n = 0; n < 2; ++n) acc[a][b][m][n] = (f32x4){0.f, 0.f, 0.f, 0.f};
;     bf16x8 At[4][2], B0[2][2], B1[2][2];
;     const char* cA = (const char*)g.A + (size_t)cur.pm * tstepA + (size_t)cur.pn * apn; const char* cB = (const char*)g.Bt + (size_t)cur.pn * tstepB;
;     S.a_ready(cur);
;     if constexpr (SP2) {
;         PG8_STAGE(PG8_SB(0, 0), cB, voffB); PG8_STAGE(PG8_SB(0, 1), cB + hstepB, voffB); PG8_STAGE(PG8_SA(0, 0), cA, voffA); PG8_STAGE(PG8_SA(0, 1), cA + hstepA, voffA);
;         if (wr == 1) PG8_BAR;
;         PG8_WAIT_V(2); PG8_BAR;
;         PG8_STAGE(PG8_SB(1, 0), cB + kstep, voffB); PG8_STAGE(PG8_SA(1, 0), cA + kstep, voffA); PG8_STAGE(PG8_SB(1, 1), cB + hstepB + kstep, voffB);
;         PG8_WAIT_V(6); PG8_BAR;
;     } else {
.LBB0_188:
	s_or_b64 exec, exec, s[0:1]
	s_add_u32 s24, s68, 0x5000000
	s_addc_u32 s25, s69, 0
	s_add_u32 s18, s68, 0x11000000
	s_addc_u32 s19, s69, 0
	s_add_u32 s42, s68, 0x19000000
	s_addc_u32 s43, s69, 0
	s_add_u32 s44, s68, 0x21000000
	s_addc_u32 s45, s69, 0
	s_add_u32 s0, s68, 0x29000000
	s_addc_u32 s1, s69, 0
	s_add_u32 s20, s68, 0x2d000000
	s_addc_u32 s21, s69, 0
	s_add_u32 s30, s68, 0x2000
	s_addc_u32 s31, s69, 0
	s_cmpk_lt_i32 s26, 0x1600
	s_waitcnt lgkmcnt(0)
	v_mov_b32_e32 v0, v174
	v_mov_b32_e32 v9, v174
	s_cselect_b64 s[2:3], -1, 0
	s_barrier
	v_writelane_b32 v238, s2, 16
	s_cmpk_gt_i32 s26, 0x15ff
	v_readfirstlane_b32 s4, v9
	v_writelane_b32 v238, s3, 17
	s_cbranch_scc1 .LBB0_227
	v_lshlrev_b32_e32 v0, 4, v9
	v_add_u32_e32 v1, 0x2000, v0
	v_ashrrev_i32_e32 v2, 31, v1
	v_lshrrev_b32_e32 v2, 22, v2
	v_add_u32_e32 v2, v1, v2
	v_ashrrev_i32_e32 v8, 10, v2
	v_mul_i32_i24_e32 v2, 0x400, v8
	v_sub_u32_e32 v1, v1, v2
	v_lshrrev_b32_e32 v2, 4, v1
	v_bitop3_b32 v1, v2, v1, 32 bitop3:0x6c
	v_ashrrev_i32_e32 v2, 31, v1
	v_lshrrev_b32_e32 v2, 26, v2
	v_add_u32_e32 v2, v1, v2
	v_lshlrev_b32_e32 v3, 3, v8
	v_ashrrev_i32_e32 v10, 6, v2
	v_and_b32_e32 v3, -16, v3
	v_add_u32_e32 v3, v10, v3
	v_and_b32_e32 v4, 3, v10
	s_mov_b32 s2, 0x1fffe0
	v_lshrrev_b32_e32 v5, 2, v3
	v_lshlrev_b32_e32 v6, 1, v3
	v_and_b32_e32 v2, 0xc0, v2
	v_and_or_b32 v4, v3, s2, v4
	v_and_b32_e32 v5, 4, v5
	v_and_b32_e32 v6, 24, v6
	v_sub_u32_e32 v1, v1, v2
	v_mov_b32_e32 v2, 1
	v_or3_b32 v4, v4, v5, v6
	v_lshlrev_b32_e32 v5, 5, v8
	v_ashrrev_i16_sdwa v1, v2, sext(v1) dst_sel:DWORD dst_unused:UNUSED_PAD src0_sel:DWORD src1_sel:BYTE_0
	v_and_b32_e32 v5, 32, v5
	v_bfe_i32 v11, v1, 0, 16
	v_add_lshl_u32 v1, v5, v11, 1
	v_lshl_add_u32 v128, v4, 11, v1
	v_lshl_add_u32 v130, v3, 11, v1
	v_bfe_i32 v1, v9, 27, 1
	v_lshrrev_b32_e32 v1, 22, v1
	v_add_u32_e32 v1, v0, v1
	v_and_b32_e32 v1, 0xfffffc00, v1
	v_sub_u32_e32 v0, v0, v1
	v_lshrrev_b32_e32 v1, 4, v0
	v_ashrrev_i32_e32 v3, 31, v9
	v_bitop3_b32 v0, v1, v0, 32 bitop3:0x6c
	v_lshrrev_b32_e32 v3, 26, v3
	v_ashrrev_i32_e32 v1, 31, v0
	v_add_u32_e32 v3, v9, v3
	v_lshrrev_b32_e32 v1, 26, v1
	v_ashrrev_i32_e32 v13, 6, v3
	v_add_u32_e32 v1, v0, v1
	v_lshlrev_b32_e32 v3, 3, v13
	v_ashrrev_i32_e32 v12, 6, v1
	v_and_b32_e32 v3, -16, v3
	v_add_u32_e32 v3, v12, v3
	v_and_b32_e32 v4, 3, v12
	s_ashr_i32 s35, s26, 31
	v_and_or_b32 v4, v3, s2, v4
	s_lshr_b32 s2, s35, 29
	s_add_i32 s2, s26, s2
	s_ashr_i32 s5, s4, 6
	s_ashr_i32 s6, s2, 3
	s_and_b32 s2, s2, -8
	s_ashr_i32 s3, s4, 8
	s_lshl_b32 s27, s5, 10
	s_sub_i32 s2, s26, s2
	s_cmp_lt_i32 s2, 0
	s_movk_i32 s41, 0x2c1
	s_cselect_b32 s7, s41, 0x2c0
	s_mul_i32 s2, s2, s7
	s_add_i32 s2, s2, s6
	s_mul_hi_i32 s6, s2, 0x2e8ba2e9
	s_lshr_b32 s7, s6, 31
	s_ashr_i32 s6, s6, 3
	s_add_i32 s6, s6, s7
	s_lshl_b32 s7, s6, 1
	s_mulk_i32 s6, 0x2c
	s_sub_i32 s6, s2, s6
	s_bfe_u32 s2, s6, 0x1001f
	s_add_i32 s8, s6, s2
	s_sext_i32_i16 s2, s8
	s_and_b32 s8, s8, 0xfffe
	s_sub_i32 s6, s6, s8
	s_sext_i32_i16 s6, s6
	v_lshrrev_b32_e32 v5, 2, v3
	v_lshlrev_b32_e32 v6, 1, v3
	v_and_b32_e32 v1, 0xc0, v1
	s_lshr_b32 s2, s2, 1
	s_add_i32 s58, s7, s6
	v_and_b32_e32 v5, 4, v5
	v_and_b32_e32 v6, 24, v6
	v_sub_u32_e32 v0, v0, v1
	s_ashr_i32 s59, s58, 31
	s_bfe_i64 s[8:9], s[2:3], 0x100000
	v_or3_b32 v4, v4, v5, v6
	v_lshlrev_b32_e32 v5, 5, v13
	v_ashrrev_i16_sdwa v0, v2, sext(v0) dst_sel:DWORD dst_unused:UNUSED_PAD src0_sel:DWORD src1_sel:BYTE_0
	s_lshl_b64 s[6:7], s[58:59], 19
	s_lshl_b64 s[8:9], s[8:9], 19
	v_and_b32_e32 v5, 32, v5
	v_bfe_i32 v14, v0, 0, 16
	s_add_u32 s66, s82, s8
	v_add_lshl_u32 v0, v5, v14, 1
	s_addc_u32 s67, s83, s9
	s_add_i32 s59, s27, 0
	v_lshl_add_u32 v132, v4, 11, v0
	s_add_i32 m0, s59, 0x10000
	v_lshl_add_u32 v134, v3, 11, v0
	global_load_lds_dwordx4 v132, s[66:67]
	s_add_i32 m0, s59, 0x12000
	s_add_u32 s8, s66, 0x40000
	global_load_lds_dwordx4 v128, s[66:67]
	s_addc_u32 s9, s67, 0
	s_add_i32 m0, s59, 0x14000
	v_writelane_b32 v238, s97, 18
	global_load_lds_dwordx4 v132, s[8:9]
	s_add_i32 m0, s59, 0x16000
	s_add_u32 s60, s24, s6
	s_addc_u32 s61, s25, s7
	s_add_i32 s86, s59, 0x2000
	global_load_lds_dwordx4 v128, s[8:9]
	s_mov_b32 m0, s59
	s_add_u32 s6, s60, 0x40000
	global_load_lds_dwordx4 v134, s[60:61]
	s_mov_b32 m0, s86
	s_addc_u32 s7, s61, 0
	s_add_i32 s87, s59, 0x4000
	global_load_lds_dwordx4 v130, s[60:61]
	s_mov_b32 m0, s87
	s_add_i32 s88, s59, 0x6000
	global_load_lds_dwordx4 v134, s[6:7]
	s_mov_b32 m0, s88
	v_mov_b32_e32 v137, 0
	global_load_lds_dwordx4 v130, s[6:7]
	v_writelane_b32 v238, s96, 19
	v_mov_b32_e32 v133, v137
	v_mov_b32_e32 v129, v137
	v_mov_b32_e32 v135, v137
	v_mov_b32_e32 v131, v137
	s_cmp_eq_u32 s3, 1
	v_writelane_b32 v238, s94, 20
	s_movk_i32 s89, 0x2000
	s_mov_b32 s90, 0
	v_lshl_add_u64 v[6:7], s[66:67], 0, v[132:133]
	v_lshl_add_u64 v[4:5], s[66:67], 0, v[128:129]
	v_lshl_add_u64 v[0:1], s[60:61], 0, v[134:135]
	s_cselect_b64 s[6:7], -1, 0
	s_cmp_lg_u32 s3, 1
	v_lshl_add_u64 v[2:3], s[60:61], 0, v[130:131]
	v_writelane_b32 v238, s95, 21
	s_cbranch_scc1 .LBB0_191
	s_barrier

;     __host__ __device__ bool next(int i, Unit& u) const {
;         const long L = (long)i * G + c; if (L >= nwg) return false;
;         int wgid = (int)L; { const int q = nwg / NXCD, r = nwg % NXCD, xcd = wgid % NXCD, off = wgid / NXCD; wgid = (xcd < r ? xcd * (q + 1) : r * (q + 1) + (xcd - r) * q) + off; }
;         const int nig = WGM * nN, gid = wgid / nig, fm = gid * WGM, gsz = (nM - fm) < WGM ? (nM - fm) : WGM;
;         u.pm = fm + ((wgid % nig) % gsz); u.pn = (wgid % nig) / gsz; return true;
; template <class Epi, class Sched, bool ALIGN_EPI = false, bool SP2 = false>
; __device__ __forceinline__ void gemm_phase(PG8_LAS unsigned char* lds, const Gemm g, const Sched& S, const Epi& E) {
;     ...
;         const bool has_next = S.next(ui + 1, nxt);
;         const char* nA = has_next ? (const char*)g.A + (size_t)nxt.pm * tstepA + (size_t)nxt.pn * apn : cA; const char* nB = has_next ? (const char*)g.Bt + (size_t)nxt.pn * tstepB : cB;
.LBB0_194:
	s_add_i32 s90, s90, 1
	s_mul_i32 s4, s90, s94
	s_mul_hi_u32 s5, s90, s95
	s_add_i32 s5, s5, s4
	s_mul_i32 s4, s90, s95
	s_add_u32 s16, s4, s26
	s_addc_u32 s17, s5, s35
	v_cmp_gt_i64_e32 vcc, s[16:17], v[144:145]
	v_cmp_lt_i64_e64 s[4:5], s[16:17], v[142:143]
	s_cbranch_vccnz .LBB0_196
	s_ashr_i32 s12, s16, 31
	s_lshr_b32 s12, s12, 29
	s_add_i32 s12, s16, s12
	s_ashr_i32 s13, s12, 3
	s_and_b32 s12, s12, -8
	s_sub_i32 s12, s16, s12
	s_cmp_lt_i32 s12, 0
	s_cselect_b32 s14, s41, 0x2c0
	s_mul_i32 s12, s12, s14
	s_add_i32 s12, s12, s13
	s_mul_hi_i32 s13, s12, 0x2e8ba2e9
	s_lshr_b32 s14, s13, 31
	s_ashr_i32 s13, s13, 3
	s_add_i32 s13, s13, s14
	s_lshl_b32 s14, s13, 1
	s_sub_i32 s15, 0x100, s14
	s_min_i32 s15, s15, 2
	s_abs_i32 s16, s15
	v_cvt_f32_u32_e32 v0, s16
	s_sub_i32 s56, 0, s16
	s_mulk_i32 s13, 0x2c
	s_sub_i32 s13, s12, s13
	v_rcp_iflag_f32_e32 v0, v0
	s_abs_i32 s12, s13
	s_xor_b32 s17, s13, s15
	s_ashr_i32 s17, s17, 31
	v_mul_f32_e32 v0, 0x4f7ffffe, v0
	v_cvt_u32_f32_e32 v0, v0
	s_nop 0
	v_readfirstlane_b32 s57, v0
	s_mul_i32 s56, s56, s57
	s_mul_hi_u32 s56, s57, s56
	s_add_i32 s57, s57, s56
	s_mul_hi_u32 s56, s12, s57
	s_mul_i32 s57, s56, s16
	s_sub_i32 s12, s12, s57
	s_add_i32 s74, s56, 1
	s_sub_i32 s57, s12, s16
	s_cmp_ge_u32 s12, s16
	s_cselect_b32 s56, s74, s56
	s_cselect_b32 s12, s57, s12
	s_add_i32 s57, s56, 1
	s_cmp_ge_u32 s12, s16
	s_cselect_b32 s12, s57, s56
	s_xor_b32 s12, s12, s17
	s_sub_i32 s12, s12, s17
	s_mul_i32 s15, s12, s15
	s_sub_i32 s13, s13, s15
	s_add_i32 s14, s14, s13

;     __host__ __device__ bool next(int i, Unit& u) const {
;         const long L = (long)i * G + c; if (L >= nwg) return false;
;         int wgid = (int)L; { const int q = nwg / NXCD, r = nwg % NXCD, xcd = wgid % NXCD, off = wgid / NXCD; wgid = (xcd < r ? xcd * (q + 1) : r * (q + 1) + (xcd - r) * q) + off; }
;         const int nig = WGM * nN, gid = wgid / nig, fm = gid * WGM, gsz = (nM - fm) < WGM ? (nM - fm) : WGM;
;         u.pm = fm + ((wgid % nig) % gsz); u.pn = (wgid % nig) / gsz; return true;
; template <class Epi, class Sched, bool ALIGN_EPI = false, bool SP2 = false>
; __device__ __forceinline__ void gemm_phase(PG8_LAS unsigned char* lds, const Gemm g, const Sched& S, const Epi& E) {
;     ...
;     for (int i = 0; i < 2; ++i) { int R, C; stage_rc(tid * 16 + i * 8192, R, C); const int Rb = Epi::PERM ? ((R & ~31) + perm32(R & 31)) : R;
;         voffA[i] = (unsigned)(R * g.lda + C) * 2u; voffB[i] = (unsigned)(Rb * g.ldb + C) * 2u; }
;     const size_t kstep = (size_t)(BK * 2);
;     const size_t hstepA = (size_t)HALF * g.lda * 2, hstepB = (size_t)HALF * g.ldb * 2;
;     const size_t tstepA = 2 * hstepA, tstepB = 2 * hstepB, apn = (size_t)g.apn;
;     const unsigned ldsw = (unsigned)wid * 1024u;
;     const int aoff = lds_byte(wr * 64 + fr, fq * 8), boff = lds_byte(wc * 32 + fr, fq * 8);
;     ...
;     Unit cur, nxt; int ui = 0;
;     if (!S.next(0, cur)) return;
;     f32x4 acc[2][2][4][2];
; #pragma unroll
;     for (int a = 0; a < 2; ++a)
; #pragma unroll
;         for (int b = 0; b < 2; ++b)
; #pragma unroll
;             for (int m = 0; m < 4; ++m)
; #pragma unroll
;                 for (int n = 0; n < 2; ++n) acc[a][b][m][n] = (f32x4){0.f, 0.f, 0.f, 0.f};
;     bf16x8 At[4][2], B0[2][2], B1[2][2];
;     const char* cA = (const char*)g.A + (size_t)cur.pm * tstepA + (size_t)cur.pn * apn; const char* cB = (const char*)g.Bt + (size_t)cur.pn * tstepB;
;     S.a_ready(cur);
;     if constexpr (SP2) {
;         PG8_STAGE(PG8_SB(0, 0), cB, voffB); PG8_STAGE(PG8_SB(0, 1), cB + hstepB, voffB); PG8_STAGE(PG8_SA(0, 0), cA, voffA); PG8_STAGE(PG8_SA(0, 1), cA + hstepA, voffA);
;         if (wr == 1) PG8_BAR;
;         PG8_WAIT_V(2); PG8_BAR;
;         PG8_STAGE(PG8_SB(1, 0), cB + kstep, voffB); PG8_STAGE(PG8_SA(1, 0), cA + kstep, voffA); PG8_STAGE(PG8_SB(1, 1), cB + hstepB + kstep, voffB);
;         PG8_WAIT_V(6); PG8_BAR;
;     } else {
.LBB0_596:
	s_or_b64 exec, exec, s[0:1]
	v_readlane_b32 s0, v238, 16
	s_waitcnt lgkmcnt(0)
	v_mov_b32_e32 v0, v174
	v_mov_b32_e32 v9, v174
	v_readlane_b32 s1, v238, 17
	s_barrier
	s_andn2_b64 vcc, exec, s[0:1]
	v_readfirstlane_b32 s3, v9
	s_cbranch_vccnz .LBB0_612
	v_lshlrev_b32_e32 v0, 4, v9
	v_add_u32_e32 v1, 0x2000, v0
	v_ashrrev_i32_e32 v2, 31, v1
	v_lshrrev_b32_e32 v2, 22, v2
	v_add_u32_e32 v2, v1, v2
	v_ashrrev_i32_e32 v8, 10, v2
	v_mul_i32_i24_e32 v2, 0x400, v8
	v_sub_u32_e32 v1, v1, v2
	v_lshrrev_b32_e32 v2, 4, v1
	v_bitop3_b32 v1, v2, v1, 32 bitop3:0x6c
	v_ashrrev_i32_e32 v2, 31, v1
	v_lshrrev_b32_e32 v2, 26, v2
	v_add_u32_e32 v2, v1, v2
	v_lshlrev_b32_e32 v3, 3, v8
	v_ashrrev_i32_e32 v10, 6, v2
	v_and_b32_e32 v3, -16, v3
	v_add_u32_e32 v3, v10, v3
	v_and_b32_e32 v4, 3, v10
	s_mov_b32 s0, 0x1fffe0
	v_lshrrev_b32_e32 v5, 2, v3
	v_lshlrev_b32_e32 v6, 1, v3
	v_and_b32_e32 v2, 0xc0, v2
	v_and_or_b32 v4, v3, s0, v4
	v_and_b32_e32 v5, 4, v5
	v_and_b32_e32 v6, 24, v6
	v_sub_u32_e32 v1, v1, v2
	v_mov_b32_e32 v2, 1
	v_or3_b32 v4, v4, v5, v6
	v_lshlrev_b32_e32 v5, 5, v8
	v_ashrrev_i16_sdwa v1, v2, sext(v1) dst_sel:DWORD dst_unused:UNUSED_PAD src0_sel:DWORD src1_sel:BYTE_0
	v_and_b32_e32 v5, 32, v5
	v_bfe_i32 v11, v1, 0, 16
	v_add_lshl_u32 v1, v5, v11, 1
	v_lshl_add_u32 v128, v4, 11, v1
	v_lshl_add_u32 v130, v3, 11, v1
	v_bfe_i32 v1, v9, 27, 1
	v_lshrrev_b32_e32 v1, 22, v1
	v_add_u32_e32 v1, v0, v1
	v_and_b32_e32 v1, 0xfffffc00, v1
	v_sub_u32_e32 v0, v0, v1
	v_lshrrev_b32_e32 v1, 4, v0
	v_ashrrev_i32_e32 v3, 31, v9
	v_bitop3_b32 v0, v1, v0, 32 bitop3:0x6c
	v_lshrrev_b32_e32 v3, 26, v3
	v_ashrrev_i32_e32 v1, 31, v0
	v_add_u32_e32 v3, v9, v3
	v_lshrrev_b32_e32 v1, 26, v1
	v_ashrrev_i32_e32 v13, 6, v3
	v_add_u32_e32 v1, v0, v1
	v_lshlrev_b32_e32 v3, 3, v13
	v_ashrrev_i32_e32 v12, 6, v1
	v_and_b32_e32 v3, -16, v3
	v_add_u32_e32 v3, v12, v3
	v_and_b32_e32 v4, 3, v12
	s_ashr_i32 s23, s26, 31
	v_and_or_b32 v4, v3, s0, v4
	s_lshr_b32 s0, s23, 29
	s_add_i32 s0, s26, s0
	s_ashr_i32 s6, s3, 6
	s_ashr_i32 s1, s0, 3
	s_and_b32 s0, s0, -8
	s_ashr_i32 s8, s3, 8
	s_lshl_b32 s22, s6, 10
	s_sub_i32 s0, s26, s0
	s_cmp_lt_i32 s0, 0
	s_movk_i32 s28, 0x2c1
	s_cselect_b32 s2, s28, 0x2c0
	s_mul_i32 s0, s0, s2
	s_add_i32 s0, s0, s1
	s_mul_hi_i32 s1, s0, 0x2e8ba2e9
	s_lshr_b32 s2, s1, 31
	s_ashr_i32 s1, s1, 3
	s_add_i32 s1, s1, s2
	s_lshl_b32 s7, s1, 1
	s_mulk_i32 s1, 0x2c
	s_sub_i32 s0, s0, s1
	s_bfe_u32 s1, s0, 0x1001f
	s_add_i32 s1, s0, s1
	s_sext_i32_i16 s2, s1
	s_and_b32 s1, s1, 0xfffe
	s_sub_i32 s0, s0, s1
	s_sext_i32_i16 s0, s0
	v_lshrrev_b32_e32 v5, 2, v3
	v_lshlrev_b32_e32 v6, 1, v3
	v_and_b32_e32 v1, 0xc0, v1
	s_lshr_b32 s2, s2, 1
	s_add_i32 s36, s7, s0
	v_and_b32_e32 v5, 4, v5
	v_and_b32_e32 v6, 24, v6
	v_sub_u32_e32 v0, v0, v1
	s_ashr_i32 s37, s36, 31
	s_bfe_i64 s[10:11], s[2:3], 0x100000
	v_or3_b32 v4, v4, v5, v6
	v_lshlrev_b32_e32 v5, 5, v13
	v_ashrrev_i16_sdwa v0, v2, sext(v0) dst_sel:DWORD dst_unused:UNUSED_PAD src0_sel:DWORD src1_sel:BYTE_0
	s_lshl_b64 s[0:1], s[36:37], 19
	s_lshl_b64 s[10:11], s[10:11], 19
	v_and_b32_e32 v5, 32, v5
	v_bfe_i32 v14, v0, 0, 16
	s_add_u32 s40, s60, s10
	v_add_lshl_u32 v0, v5, v14, 1
	s_addc_u32 s41, s61, s11
	s_add_i32 s29, s22, 0
	v_lshl_add_u32 v132, v4, 11, v0
	s_add_i32 m0, s29, 0x10000
	v_lshl_add_u32 v134, v3, 11, v0
	global_load_lds_dwordx4 v132, s[40:41]
	s_add_i32 m0, s29, 0x12000
	s_add_u32 s10, s40, 0x40000
	global_load_lds_dwordx4 v128, s[40:41]
	s_addc_u32 s11, s41, 0
	s_add_i32 m0, s29, 0x14000
	v_mov_b32_e32 v133, 0
	global_load_lds_dwordx4 v132, s[10:11]
	s_add_i32 m0, s29, 0x16000
	s_add_u32 s38, s24, s0
	s_addc_u32 s39, s25, s1
	s_add_i32 s30, s29, 0x2000
	global_load_lds_dwordx4 v128, s[10:11]
	s_mov_b32 m0, s29
	s_add_u32 s0, s38, 0x40000
	global_load_lds_dwordx4 v134, s[38:39]
	s_mov_b32 m0, s30
	s_addc_u32 s1, s39, 0
	s_add_i32 s31, s29, 0x4000
	global_load_lds_dwordx4 v130, s[38:39]
	s_mov_b32 m0, s31
	s_add_i32 s35, s29, 0x6000
	global_load_lds_dwordx4 v134, s[0:1]
	s_mov_b32 m0, s35
	v_mov_b32_e32 v129, v133
	global_load_lds_dwordx4 v130, s[0:1]
	v_mov_b32_e32 v135, v133
	v_mov_b32_e32 v131, v133
	s_cmp_eq_u32 s8, 1
	s_mov_b32 s37, 0
	v_lshl_add_u64 v[6:7], s[40:41], 0, v[132:133]
	v_lshl_add_u64 v[4:5], s[40:41], 0, v[128:129]
	v_lshl_add_u64 v[0:1], s[38:39], 0, v[134:135]
	s_cselect_b64 s[0:1], -1, 0
	s_cmp_lg_u32 s8, 1
	v_lshl_add_u64 v[2:3], s[38:39], 0, v[130:131]
	s_cbranch_scc1 .LBB0_599
	s_barrier

;     __host__ __device__ bool next(int i, Unit& u) const {
;         const long L = (long)i * G + c; if (L >= nwg) return false;
;         int wgid = (int)L; { const int q = nwg / NXCD, r = nwg % NXCD, xcd = wgid % NXCD, off = wgid / NXCD; wgid = (xcd < r ? xcd * (q + 1) : r * (q + 1) + (xcd - r) * q) + off; }
;         const int nig = WGM * nN, gid = wgid / nig, fm = gid * WGM, gsz = (nM - fm) < WGM ? (nM - fm) : WGM;
;         u.pm = fm + ((wgid % nig) % gsz); u.pn = (wgid % nig) / gsz; return true;
; template <class Epi, class Sched, bool ALIGN_EPI = false, bool SP2 = false>
; __device__ __forceinline__ void gemm_phase(PG8_LAS unsigned char* lds, const Gemm g, const Sched& S, const Epi& E) {
;     ...
;         const bool has_next = S.next(ui + 1, nxt);
;         const char* nA = has_next ? (const char*)g.A + (size_t)nxt.pm * tstepA + (size_t)nxt.pn * apn : cA; const char* nB = has_next ? (const char*)g.Bt + (size_t)nxt.pn * tstepB : cB;
.LBB0_602:
	s_add_i32 s37, s37, 1
	s_mul_i32 s2, s37, s46
	s_mul_hi_u32 s3, s37, s47
	s_add_i32 s3, s3, s2
	s_mul_i32 s2, s37, s47
	s_add_u32 s14, s2, s26
	s_addc_u32 s15, s3, s23
	v_cmp_gt_i64_e32 vcc, s[14:15], v[142:143]
	v_cmp_lt_i64_e64 s[2:3], s[14:15], v[140:141]
	s_cbranch_vccnz .LBB0_604
	s_ashr_i32 s10, s14, 31
	s_lshr_b32 s10, s10, 29
	s_add_i32 s10, s14, s10
	s_ashr_i32 s11, s10, 3
	s_and_b32 s10, s10, -8
	s_sub_i32 s10, s14, s10
	s_cmp_lt_i32 s10, 0
	s_cselect_b32 s12, s28, 0x2c0
	s_mul_i32 s10, s10, s12
	s_add_i32 s10, s10, s11
	s_mul_hi_i32 s11, s10, 0x2e8ba2e9
	s_lshr_b32 s12, s11, 31
	s_ashr_i32 s11, s11, 3
	s_add_i32 s11, s11, s12
	s_lshl_b32 s12, s11, 1
	s_sub_i32 s13, 0x100, s12
	s_min_i32 s13, s13, 2
	s_abs_i32 s14, s13
	v_cvt_f32_u32_e32 v0, s14
	s_sub_i32 s16, 0, s14
	s_mulk_i32 s11, 0x2c
	s_sub_i32 s11, s10, s11
	v_rcp_iflag_f32_e32 v0, v0
	s_abs_i32 s10, s11
	s_xor_b32 s15, s11, s13
	s_ashr_i32 s15, s15, 31
	v_mul_f32_e32 v0, 0x4f7ffffe, v0
	v_cvt_u32_f32_e32 v0, v0
	s_nop 0
	v_readfirstlane_b32 s17, v0
	s_mul_i32 s16, s16, s17
	s_mul_hi_u32 s16, s17, s16
	s_add_i32 s17, s17, s16
	s_mul_hi_u32 s16, s10, s17
	s_mul_i32 s17, s16, s14
	s_sub_i32 s10, s10, s17
	s_add_i32 s33, s16, 1
	s_sub_i32 s17, s10, s14
	s_cmp_ge_u32 s10, s14
	s_cselect_b32 s16, s33, s16
	s_cselect_b32 s10, s17, s10
	s_add_i32 s17, s16, 1
	s_cmp_ge_u32 s10, s14
	s_cselect_b32 s10, s17, s16
	s_xor_b32 s10, s10, s15
	s_sub_i32 s10, s10, s15
	s_mul_i32 s13, s10, s13
	s_sub_i32 s11, s11, s13
	s_add_i32 s12, s12, s11
